# phase G (layers 0-2): workgroups 0..127 run [full tile, K-split tail slice, full tile] instead of [full, full, tail], de-phasing their second read-modify-write epilogue from the other half's
# baseline (speedup 1.0000x reference)
;     __device__ __forceinline__ bool next(int i, Unit& u) const {
;         const int L = i * G + c; const int ntail = nunits - nfull;
;         if (L < nfull) { u.batch = 0; u.aux = 0; std_map(L, 136, 4, u.pm, u.pn); return true; }
;         const int j = L - nfull; if (j >= ntail * NS) return false;
;         u.batch = 1 + j / ntail; u.aux = j % ntail; std_map(nfull + u.aux, 136, 4, u.pm, u.pn); return true;
;     }
; __global__ __launch_bounds__(512, 2) void mega(Args a_) {
;     ...
;             else pg8::gemm_phase(lds, pg8::TailProb<4>(WSP(OFF_HN), WSP(OFF_WA + WA_WOUT), DM, DM, G, c, G == 256), E);
.LBB0_990:
	s_add_i32 s33, s33, 1
	s_mov_b32 s0, s33
	s_cmpk_lg_i32 s6, 0x100
	s_cbranch_scc1 .Ltail_ord_1
	s_cmpk_gt_i32 s46, 0x7f
	s_cbranch_scc1 .Ltail_ord_1
	s_cmpk_gt_i32 s33, 2
	s_cbranch_scc1 .Ltail_ord_1
	s_sub_i32 s0, 3, s33
.Ltail_ord_1:
	s_mul_i32 s0, s0, s6
	s_add_i32 s5, s0, s46
	s_cmp_lt_i32 s5, s61
	s_mov_b64 s[0:1], -1
	s_cbranch_scc1 .LBB0_993
	s_sub_i32 s16, s5, s61
	s_cmp_lt_i32 s16, s3
	s_mov_b64 s[0:1], 0
	s_cbranch_scc0 .LBB0_994
	s_abs_i32 s1, s16
	s_mul_hi_u32 s5, s1, s56
	s_mul_i32 s17, s5, s19
	s_ashr_i32 s0, s16, 31
	s_sub_i32 s1, s1, s17
	s_xor_b32 s0, s0, s18
	s_add_i32 s17, s5, 1
	s_sub_i32 s34, s1, s19
	s_cmp_ge_u32 s1, s19
	s_cselect_b32 s5, s17, s5
	s_cselect_b32 s1, s34, s1
	s_add_i32 s17, s5, 1
	s_cmp_ge_u32 s1, s19
	s_cselect_b32 s1, s17, s5
	s_xor_b32 s1, s1, s0
	s_sub_i32 s0, s1, s0
	s_add_i32 s64, s0, 1
	s_mul_i32 s0, s0, s62
	s_sub_i32 s72, s16, s0
	s_add_i32 s5, s72, s61
	s_mov_b64 s[0:1], -1
	s_branch .LBB0_994
